# plus: dropped the m0 save and restore around each LDS-DMA issue in the attention unit (m0 has no other reader)
# baseline (speedup 1.0000x reference)
; #define WAIT_BAR(N) asm volatile("s_waitcnt vmcnt(" #N ") lgkmcnt(0)\n\ts_barrier":::"memory")
;   #define DMA_K(t,slot) glds16(ksrc+(long)(t)*KVBLK*PZ,(unsigned)__builtin_amdgcn_readfirstlane(kdst+(slot)))
;   #define DMA_V(t,slot) do{ glds16(vsrc+(long)(t)*KVBLK*PZ,(unsigned)__builtin_amdgcn_readfirstlane(vdst+(slot))); glds16(vsrc+(long)SEQ*PZ+(long)(t)*KVBLK*PZ,(unsigned)__builtin_amdgcn_readfirstlane(vdst+NSLOT*SLOTB+(slot))); }while(0)
;   #define CMASK(P0,P1,t) do{int jb_=(t)-(NT-4); if(jb_>=0)cmask(P0,P1,jb_,qrel,hi);}while(0)
;   #define CMASK(P0,P1,t) do{}while(0)
;   #define CMASK(P0,P1,t) do{int jb_=(t)-(NT-4); if(jb_>=0)cmask(P0,P1,jb_,qrel,hi);}while(0)
; template<int THRL> __device__ __forceinline__ void attn_unit(int qb,const bf16*Q,const bf16*__restrict__ K,const bf16*__restrict__ V,bf16*O,char*shm){
;   int tid=threadIdx.x; asm volatile("":"+v"(tid)); const int lane=tid&63,r32=lane&31,hi=lane>>5; const int wid=__builtin_amdgcn_readfirstlane(tid>>6);
;   const int q0=qb*QB;
;   const bf16*Qw=Q+(long)(q0+wid*QBLK)*PZ;
;   const bf16*Kh=K,*Vh=V;
;   const unsigned lds0=(unsigned)(uintptr_t)shm;
;   float*wsf=(float*)(shm+LDS_WS)+wid*64;
;   const bf16*ksrc=Kh+(long)lane*PZ+wid*8;
;   const bf16*vsrc=Vh+(long)(16*(wid&3)+(lane>>2))*PZ+(wid>>2)*32+(lane&3)*8;
;   const unsigned kdst=lds0+LDS_K+wid*1024, vdst=lds0+LDS_V+wid*1024;
;     ...
;   const int vb0=(int)(lds0+LDS_V)+((lane>>4)&1)*32+(lane&3)*8+(4*hi+((lane&15)>>2))*64;
;   const char*Kbase=shm+LDS_K; bf16x8 kf[8];
;   const lds_cptr shm3=(lds_cptr)shm; const lds_cptr kp0=shm3+LDS_K+hi*1024+r32*16; const lds_cptr vp0=shm3+LDS_V+((lane>>4)&1)*32+(lane&3)*8+(4*hi+((lane&15)>>2))*64;
;   const int NT=(q0+QB)/KVBLK;
;   DMA_K(0,0);DMA_V(0,0);DMA_K(1,SLOTB);
;   bf16x8 qr[4];
;   #pragma unroll
;   for(int d0=0;d0<4;++d0)qr[d0]=*reinterpret_cast<const bf16x8*>(&Qw[(long)r32*PZ+d0*16+hi*8]);
;   float mhat=0.f,l_reg=0.f;f32x16 o[4];o[0]=f32x16{};o[1]=f32x16{};o[2]=f32x16{};o[3]=f32x16{};f32x16 negm=f32x16{};asm volatile("":"+v"(negm));
;   const int qrel=wid*QBLK+r32;
;     ...
;   bool resc=false;
;     ...
;   f32x16 pA0,pA1,pB0,pB1;
;   int sl_prev=0,sl_cur=0,sl_next=SLOTB;
;     ...
;   DMA_K(2,2*SLOTB);
;   WAIT_BAR(4);
;   qkt(pA0,pA1,Kbase,qr,negm,r32,hi);asm volatile("s_nop 15\n\ts_nop 7":"+v"(pA0),"+v"(pA1));CMASK(pA0,pA1,0);
.LBB0_1013:
	s_bitcmp0_b32 s70, 0
	s_cselect_b32 s14, s58, s19
	s_mul_i32 s0, s70, s60
	s_add_i32 s72, s14, s0
	s_cmpk_gt_i32 s72, 0x1ff
	s_cbranch_scc1 .LBB0_1012
	s_lshl_b32 s2, s72, 19
	s_ashr_i32 s11, s72, 5
	s_bfe_u32 s73, s72, 0x20003
	s_and_b32 s0, s2, 0xf80000
	s_add_u32 s10, s20, s0
	s_addc_u32 s13, s21, 0
	s_add_u32 s0, s22, s0
	s_addc_u32 s1, s23, 0
	s_and_b32 s2, s2, 0x300000
	s_lshl_b32 s3, s73, 22
	s_or_b32 s2, s3, s2
	v_mov_b32_e32 v36, v230
	s_add_u32 s2, s59, s2
	s_addc_u32 s3, s61, 0
	v_readfirstlane_b32 s15, v36
	s_ashr_i32 s71, s15, 6
	s_lshl_b32 s16, s11, 8
	s_lshl_b32 s17, s71, 5
	s_sub_i32 s6, s17, s16
	s_addk_i32 s6, 0xf00
	s_ashr_i32 s7, s6, 31
	v_and_b32_e32 v247, 63, v36
	s_lshl_b64 s[8:9], s[6:7], 7
	s_add_u32 s12, s10, s8
	v_lshlrev_b32_e32 v220, 7, v247
	s_addc_u32 s13, s13, s9
	v_lshl_add_u64 v[0:1], s[0:1], 0, v[220:221]
	s_lshl_b32 s0, s71, 3
	s_ashr_i32 s1, s0, 31
	s_lshl_b32 s8, s71, 4
	v_bfe_u32 v224, v36, 2, 4
	v_lshl_add_u64 v[32:33], s[0:1], 1, v[0:1]
	v_and_or_b32 v0, s8, 48, v224
	v_lshlrev_b32_e32 v0, 7, v0
	v_mov_b32_e32 v1, v221
	v_lshl_add_u64 v[0:1], s[2:3], 0, v[0:1]
	s_ashr_i32 s2, s15, 3
	s_and_b32 s8, s2, 0xffffffe0
	s_ashr_i32 s9, s8, 31
	s_lshl_b32 s10, s71, 10
	v_lshlrev_b32_e32 v249, 3, v36
	s_cmp_lg_u32 0, -1
	v_and_b32_e32 v250, 24, v249
	s_cselect_b32 s2, 0, 0
	v_lshl_add_u64 v[0:1], s[8:9], 1, v[0:1]
	v_lshlrev_b32_e32 v2, 1, v250
	v_mov_b32_e32 v3, v221
	s_add_i32 s28, s10, s2
	s_mov_b32 m0, s28
	s_nop 0
	global_load_lds_dwordx4 v[32:33], off
	v_lshl_add_u64 v[34:35], v[0:1], 0, v[2:3]
	s_add_i32 s33, s28, 0x6000
	s_mov_b32 m0, s33
	s_nop 0
	global_load_lds_dwordx4 v[34:35], off
	s_mov_b64 s[2:3], 0x80000
	v_lshl_add_u64 v[0:1], v[34:35], 0, s[2:3]
	s_add_i32 s37, s28, 0xc000
	s_mov_b32 m0, s37
	s_nop 0
	global_load_lds_dwordx4 v[0:1], off
	s_mov_b64 s[2:3], 0x2000
	v_and_b32_e32 v248, 31, v36
	v_lshl_add_u64 v[0:1], v[32:33], 0, s[2:3]
	v_bfe_u32 v246, v36, 5, 1
	s_add_i32 s2, s28, 0x2000
	s_mov_b32 m0, s2
	s_nop 0
	global_load_lds_dwordx4 v[0:1], off
	v_lshlrev_b32_e32 v0, 7, v248
	v_lshl_or_b32 v0, v246, 4, v0
	v_mov_b32_e32 v1, v221
	v_lshl_add_u64 v[14:15], s[12:13], 0, v[0:1]
	flat_load_dwordx4 v[172:175], v[14:15]
	flat_load_dwordx4 v[168:171], v[14:15] offset:32
	flat_load_dwordx4 v[156:159], v[14:15] offset:64
	flat_load_dwordx4 v[148:151], v[14:15] offset:96
	v_mov_b32_e32 v0, v221
	v_mov_b32_e32 v2, v221
	v_mov_b32_e32 v4, v221
	v_mov_b32_e32 v5, v221
	v_mov_b32_e32 v6, v221
	v_mov_b32_e32 v7, v221
	v_mov_b32_e32 v8, v221
	v_mov_b32_e32 v9, v221
	v_mov_b32_e32 v10, v221
	v_mov_b32_e32 v11, v221
	v_mov_b32_e32 v12, v221
	v_mov_b32_e32 v13, v221
	v_mov_b32_e32 v14, v221
	v_mov_b32_e32 v15, v221
	v_lshlrev_b32_e32 v16, 10, v246
	v_lshlrev_b32_e32 v17, 4, v248
	v_add3_u32 v243, 0, v16, v17
	v_lshl_add_u64 v[16:17], v[32:33], 0, s[34:35]
	s_add_i32 s2, s28, 0x4000
	s_mov_b32 m0, s2
	s_nop 0
	global_load_lds_dwordx4 v[16:17], off
	s_waitcnt vmcnt(4) lgkmcnt(0)
	s_barrier
	ds_read_b128 v[38:41], v243
	s_cmp_lg_u32 s11, 15
	s_cselect_b64 s[2:3], -1, 0
	v_lshlrev_b32_e32 v254, 2, v246
	v_or_b32_e32 v241, s17, v248
	s_and_b64 vcc, exec, s[2:3]
	s_waitcnt vmcnt(0) lgkmcnt(0)
	v_mfma_f32_32x32x16_bf16 v[16:31], v[38:41], v[172:175], v[0:15]
	ds_read_b128 v[38:41], v243 offset:512
	s_waitcnt lgkmcnt(0)
	v_mfma_f32_32x32x16_bf16 v[0:15], v[38:41], v[172:175], v[0:15]
	ds_read_b128 v[38:41], v243 offset:2048
	s_waitcnt lgkmcnt(0)
	v_mfma_f32_32x32x16_bf16 v[16:31], v[38:41], v[168:171], v[16:31]
	ds_read_b128 v[38:41], v243 offset:2560
	s_waitcnt lgkmcnt(0)
	v_mfma_f32_32x32x16_bf16 v[0:15], v[38:41], v[168:171], v[0:15]
	ds_read_b128 v[38:41], v243 offset:4096
	s_waitcnt lgkmcnt(0)
	v_mfma_f32_32x32x16_bf16 v[16:31], v[38:41], v[156:159], v[16:31]
	ds_read_b128 v[38:41], v243 offset:4608
	s_waitcnt lgkmcnt(0)
	v_mfma_f32_32x32x16_bf16 v[0:15], v[38:41], v[156:159], v[0:15]
	ds_read_b128 v[38:41], v243 offset:6144
	s_waitcnt lgkmcnt(0)
	v_mfma_f32_32x32x16_bf16 v[16:31], v[38:41], v[148:151], v[16:31]
	ds_read_b128 v[38:41], v243 offset:6656
	s_waitcnt lgkmcnt(0)
	v_mfma_f32_32x32x16_bf16 v[0:15], v[38:41], v[148:151], v[0:15]
	s_nop 15
	s_nop 7
	s_cbranch_vccnz .LBB0_1016
	v_or_b32_e32 v37, 32, v254
	v_cmp_le_i32_e32 vcc, v37, v241
	v_or_b32_e32 v37, 33, v254
	s_nop 7
	v_cndmask_b32_e32 v0, v234, v0, vcc
	v_cmp_lt_i32_e32 vcc, v254, v241
	s_nop 1
	v_cndmask_b32_e32 v17, v234, v17, vcc
	v_cmp_le_i32_e32 vcc, v254, v241
	s_nop 1
	v_cndmask_b32_e32 v16, v234, v16, vcc
	v_cmp_le_i32_e32 vcc, v37, v241
	v_or_b32_e32 v37, 2, v254
	s_nop 0
	v_cndmask_b32_e32 v1, v234, v1, vcc
	v_cmp_le_i32_e32 vcc, v37, v241
	v_or_b32_e32 v37, 34, v254
	s_nop 0
	v_cndmask_b32_e32 v18, v234, v18, vcc
	v_cmp_le_i32_e32 vcc, v37, v241
	v_or_b32_e32 v37, 3, v254
	s_nop 0
	v_cndmask_b32_e32 v2, v234, v2, vcc
	v_cmp_le_i32_e32 vcc, v37, v241
	v_or_b32_e32 v37, 35, v254
	s_nop 0
	v_cndmask_b32_e32 v19, v234, v19, vcc
	v_cmp_le_i32_e32 vcc, v37, v241
	v_or_b32_e32 v37, 8, v254
	s_nop 0
	v_cndmask_b32_e32 v3, v234, v3, vcc
	v_cmp_le_i32_e32 vcc, v37, v241
	v_or_b32_e32 v37, 40, v254
	s_nop 0
	v_cndmask_b32_e32 v20, v234, v20, vcc
	v_cmp_le_i32_e32 vcc, v37, v241
	v_or_b32_e32 v37, 9, v254
	s_nop 0
	v_cndmask_b32_e32 v4, v234, v4, vcc
	v_cmp_le_i32_e32 vcc, v37, v241
	v_or_b32_e32 v37, 41, v254
	s_nop 0
	v_cndmask_b32_e32 v21, v234, v21, vcc
	v_cmp_le_i32_e32 vcc, v37, v241
	v_or_b32_e32 v37, 10, v254
	s_nop 0
	v_cndmask_b32_e32 v5, v234, v5, vcc
	v_cmp_le_i32_e32 vcc, v37, v241
	v_or_b32_e32 v37, 42, v254
	s_nop 0
	v_cndmask_b32_e32 v22, v234, v22, vcc
	v_cmp_le_i32_e32 vcc, v37, v241
	v_or_b32_e32 v37, 11, v254
; #define WAIT_BAR(N) asm volatile("s_waitcnt vmcnt(" #N ") lgkmcnt(0)\n\ts_barrier":::"memory")
;   #define DMA_K(t,slot) glds16(ksrc+(long)(t)*KVBLK*PZ,(unsigned)__builtin_amdgcn_readfirstlane(kdst+(slot)))
;   #define DMA_V(t,slot) do{ glds16(vsrc+(long)(t)*KVBLK*PZ,(unsigned)__builtin_amdgcn_readfirstlane(vdst+(slot))); glds16(vsrc+(long)SEQ*PZ+(long)(t)*KVBLK*PZ,(unsigned)__builtin_amdgcn_readfirstlane(vdst+NSLOT*SLOTB+(slot))); }while(0)
;   #define CMASK(P0,P1,t) do{int jb_=(t)-(NT-4); if(jb_>=0)cmask(P0,P1,jb_,qrel,hi);}while(0)
;   #define START(P0,P1) do{ const float rm=rowmax(P0,P1); resc=false; \
;     { const float dl=rm; mhat=fadd_s(mhat,dl); \
;       _Pragma("unroll") for(int r=0;r<16;++r){P0[r]=fsub_s(P0[r],dl);P1[r]=fsub_s(P1[r],dl);} \
;       _Pragma("unroll") for(int r=0;r<16;++r)negm[r]=-mhat; asm volatile("":"+v"(negm)); } \
;     _Pragma("unroll") for(int r=0;r<16;++r)P0[r]=__builtin_amdgcn_exp2f(P0[r]); }while(0)
;   #define ROT() do{sl_prev=sl_cur;sl_cur=sl_next;sl_next=(sl_next==(NSLOT-1)*SLOTB)?0:sl_next+SLOTB;}while(0)
;   #define CMASK(P0,P1,t) do{}while(0)
;   #define CMASK(P0,P1,t) do{int jb_=(t)-(NT-4); if(jb_>=0)cmask(P0,P1,jb_,qrel,hi);}while(0)
; __device__ __forceinline__ void cmask(f32x16&p0,f32x16&p1,int jb,int qrel,int hi){
;   const float NEG=-INFINITY; int kb=64*jb+4*hi;
;   #pragma unroll
;   for(int r=0;r<16;++r){int kv=kb+(r&3)+8*(r>>2); if(kv>qrel)p0[r]=NEG; if(kv+32>qrel)p1[r]=NEG;}
; }
; template<int THRL> __device__ __forceinline__ void attn_unit(int qb,const bf16*Q,const bf16*__restrict__ K,const bf16*__restrict__ V,bf16*O,char*shm){
;     ...
;   f32x16 pA0,pA1,pB0,pB1;
;   int sl_prev=0,sl_cur=0,sl_next=SLOTB;
;     ...
;   DMA_K(2,2*SLOTB);
;   WAIT_BAR(4);
;   qkt(pA0,pA1,Kbase,qr,negm,r32,hi);asm volatile("s_nop 15\n\ts_nop 7":"+v"(pA0),"+v"(pA1));CMASK(pA0,pA1,0);
;   START(pA0,pA1);
;   _Pragma("unroll") for(int r=0;r<16;++r)pA1[r]=__builtin_amdgcn_exp2f(pA1[r]);
;   WAIT_BAR(0);
;   DMA_K(3,0);DMA_V(1,SLOTB);
;   ROT();
;   kload8(kf,kp0+sl_cur);
;   WAIT_BAR(3);
	s_nop 0
	v_cndmask_b32_e32 v6, v234, v6, vcc
	v_cmp_le_i32_e32 vcc, v37, v241
	v_or_b32_e32 v37, 43, v254
	s_nop 0
	v_cndmask_b32_e32 v23, v234, v23, vcc
	v_cmp_le_i32_e32 vcc, v37, v241
	v_or_b32_e32 v37, 16, v254
	s_nop 0
	v_cndmask_b32_e32 v7, v234, v7, vcc
	v_cmp_le_i32_e32 vcc, v37, v241
	v_or_b32_e32 v37, 48, v254
	s_nop 0
	v_cndmask_b32_e32 v24, v234, v24, vcc
	v_cmp_le_i32_e32 vcc, v37, v241
	v_or_b32_e32 v37, 17, v254
	s_nop 0
	v_cndmask_b32_e32 v8, v234, v8, vcc
	v_cmp_le_i32_e32 vcc, v37, v241
	v_or_b32_e32 v37, 49, v254
	s_nop 0
	v_cndmask_b32_e32 v25, v234, v25, vcc
	v_cmp_le_i32_e32 vcc, v37, v241
	v_or_b32_e32 v37, 18, v254
	s_nop 0
	v_cndmask_b32_e32 v9, v234, v9, vcc
	v_cmp_le_i32_e32 vcc, v37, v241
	v_or_b32_e32 v37, 50, v254
	s_nop 0
	v_cndmask_b32_e32 v26, v234, v26, vcc
	v_cmp_le_i32_e32 vcc, v37, v241
	v_or_b32_e32 v37, 19, v254
	s_nop 0
	v_cndmask_b32_e32 v10, v234, v10, vcc
	v_cmp_le_i32_e32 vcc, v37, v241
	v_or_b32_e32 v37, 51, v254
	s_nop 0
	v_cndmask_b32_e32 v27, v234, v27, vcc
	v_cmp_le_i32_e32 vcc, v37, v241
	v_or_b32_e32 v37, 24, v254
	s_nop 0
	v_cndmask_b32_e32 v11, v234, v11, vcc
	v_cmp_le_i32_e32 vcc, v37, v241
	v_or_b32_e32 v37, 56, v254
	s_nop 0
	v_cndmask_b32_e32 v28, v234, v28, vcc
	v_cmp_le_i32_e32 vcc, v37, v241
	v_or_b32_e32 v37, 25, v254
	s_nop 0
	v_cndmask_b32_e32 v12, v234, v12, vcc
	v_cmp_le_i32_e32 vcc, v37, v241
	v_or_b32_e32 v37, 57, v254
	s_nop 0
	v_cndmask_b32_e32 v29, v234, v29, vcc
	v_cmp_le_i32_e32 vcc, v37, v241
	v_or_b32_e32 v37, 26, v254
	s_nop 0
	v_cndmask_b32_e32 v13, v234, v13, vcc
	v_cmp_le_i32_e32 vcc, v37, v241
	v_or_b32_e32 v37, 58, v254
	s_nop 0
	v_cndmask_b32_e32 v30, v234, v30, vcc
	v_cmp_le_i32_e32 vcc, v37, v241
	v_or_b32_e32 v37, 27, v254
	s_nop 0
	v_cndmask_b32_e32 v14, v234, v14, vcc
	v_cmp_le_i32_e32 vcc, v37, v241
	v_or_b32_e32 v37, 59, v254
	s_nop 0
	v_cndmask_b32_e32 v31, v234, v31, vcc
	v_cmp_le_i32_e32 vcc, v37, v241
	s_nop 1
	v_cndmask_b32_e32 v15, v234, v15, vcc
.LBB0_1016:
	v_lshlrev_b32_e32 v37, 1, v36
	v_and_b32_e32 v253, 32, v37
	v_lshlrev_b32_e32 v37, 4, v36
	v_and_b32_e32 v37, 0xc0, v37
	v_lshl_or_b32 v251, v246, 8, v37
	v_add_u32_e32 v37, 0, v253
	v_add3_u32 v239, v37, v250, v251
	v_max3_f32 v37, v16, v17, v0
	v_max3_f32 v38, v18, v19, v1
	s_and_b32 s11, s15, 0x3fffffc0
	v_max3_f32 v37, v37, v2, v3
	v_max3_f32 v38, v38, v22, v23
	s_lshl_b32 s11, s11, 2
	v_max3_f32 v37, v37, v20, v21
	v_max3_f32 v38, v38, v6, v7
	s_sub_i32 s12, 0x1000, s16
	v_max3_f32 v37, v37, v4, v5
	v_max3_f32 v38, v38, v26, v27
	s_add_i32 s27, s11, 0
	v_max3_f32 v37, v37, v24, v25
	v_max3_f32 v38, v38, v10, v11
	s_add_i32 s27, s27, 0x12000
	v_max3_f32 v37, v37, v8, v9
	v_max3_f32 v38, v38, v30, v31
	s_lshr_b32 s39, s12, 6
	v_max3_f32 v37, v37, v28, v29
	v_max3_f32 v38, v38, v14, v15
	s_mov_b64 s[12:13], 0x6000
	v_max3_f32 v37, v37, v12, v13
	s_cmp_lg_u32 0, -1
	v_max_f32_e32 v37, v37, v38
	s_mov_b32 s30, 1
	v_mov_b32_e32 v38, v37
	s_nop 1
	v_permlane32_swap_b32_e32 v37, v38
	v_max_f32_e32 v37, v37, v38
	s_mov_b32 s17, 0
	v_add_f32_e32 v242, v221, v37
	v_sub_f32_e32 v0, v0, v37
	v_sub_f32_e32 v1, v1, v37
	v_sub_f32_e32 v16, v16, v37
	v_sub_f32_e32 v17, v17, v37
	v_sub_f32_e32 v18, v18, v37
	s_nop 0
	v_xor_b32_e32 v64, 0x80000000, v242
	v_mov_b32_e32 v65, v64
	v_mov_b32_e32 v66, v64
	v_mov_b32_e32 v67, v64
	v_mov_b32_e32 v68, v64
	v_mov_b32_e32 v69, v64
	v_mov_b32_e32 v70, v64
	v_mov_b32_e32 v71, v64
	v_mov_b32_e32 v72, v64
	v_mov_b32_e32 v73, v64
	v_mov_b32_e32 v74, v64
	v_mov_b32_e32 v75, v64
	v_mov_b32_e32 v76, v64
	v_mov_b32_e32 v77, v64
	v_mov_b32_e32 v78, v64
	v_mov_b32_e32 v79, v64
	s_waitcnt vmcnt(0) lgkmcnt(0)
	s_barrier
	v_exp_f32_e32 v80, v0
	v_exp_f32_e32 v81, v1
	v_lshl_add_u64 v[0:1], v[32:33], 0, s[12:13]
	s_mov_b32 m0, s28
	s_nop 0
	global_load_lds_dwordx4 v[0:1], off
	s_mov_b64 s[12:13], 0x2000
	s_cselect_b32 s11, 0, 0
	v_lshl_add_u64 v[0:1], v[34:35], 0, s[12:13]
	s_add_i32 s12, s11, s10
	s_add_i32 s10, s12, 0x8000
	s_mov_b32 m0, s10
	s_nop 0
	global_load_lds_dwordx4 v[0:1], off
	s_mov_b64 s[10:11], 0x82000
	v_lshl_add_u64 v[0:1], v[34:35], 0, s[10:11]
	s_add_i32 s12, s12, 0xe000
	s_mov_b32 m0, s12
	s_nop 0
	global_load_lds_dwordx4 v[0:1], off
	ds_read_b128 v[204:207], v243 offset:8192
	ds_read_b128 v[200:203], v243 offset:8704
	ds_read_b128 v[196:199], v243 offset:10240
	ds_read_b128 v[192:195], v243 offset:10752
	ds_read_b128 v[188:191], v243 offset:12288
	ds_read_b128 v[184:187], v243 offset:12800
	ds_read_b128 v[180:183], v243 offset:14336
	ds_read_b128 v[176:179], v243 offset:14848
	v_sub_f32_e32 v2, v2, v37
	v_sub_f32_e32 v19, v19, v37
	v_sub_f32_e32 v3, v3, v37
	v_sub_f32_e32 v20, v20, v37
	v_sub_f32_e32 v4, v4, v37
	v_sub_f32_e32 v21, v21, v37
	v_sub_f32_e32 v5, v5, v37
	v_sub_f32_e32 v22, v22, v37
	v_sub_f32_e32 v6, v6, v37
	v_sub_f32_e32 v23, v23, v37
	v_sub_f32_e32 v7, v7, v37
	v_sub_f32_e32 v24, v24, v37
	v_sub_f32_e32 v8, v8, v37
	v_sub_f32_e32 v25, v25, v37
	v_sub_f32_e32 v9, v9, v37
	v_sub_f32_e32 v26, v26, v37
	v_sub_f32_e32 v10, v10, v37
	v_sub_f32_e32 v27, v27, v37
	v_sub_f32_e32 v11, v11, v37
	v_sub_f32_e32 v28, v28, v37
	v_sub_f32_e32 v12, v12, v37
	v_sub_f32_e32 v29, v29, v37
	v_sub_f32_e32 v13, v13, v37
	v_sub_f32_e32 v30, v30, v37
	v_sub_f32_e32 v14, v14, v37
	v_sub_f32_e32 v31, v31, v37
	v_sub_f32_e32 v15, v15, v37
	v_exp_f32_e32 v96, v16
	v_exp_f32_e32 v97, v17
	v_exp_f32_e32 v98, v18
	v_exp_f32_e32 v99, v19
	v_exp_f32_e32 v100, v20
	v_exp_f32_e32 v101, v21
	v_exp_f32_e32 v102, v22
	v_exp_f32_e32 v103, v23
	v_exp_f32_e32 v104, v24
	v_exp_f32_e32 v105, v25
	v_exp_f32_e32 v106, v26
	v_exp_f32_e32 v107, v27
	v_exp_f32_e32 v108, v28
	v_exp_f32_e32 v109, v29
	v_exp_f32_e32 v110, v30
	v_exp_f32_e32 v111, v31
	v_exp_f32_e32 v82, v2
	v_exp_f32_e32 v83, v3
	v_exp_f32_e32 v84, v4
	v_exp_f32_e32 v85, v5
	v_exp_f32_e32 v86, v6
	v_exp_f32_e32 v87, v7
	v_exp_f32_e32 v88, v8
	v_exp_f32_e32 v89, v9
	v_exp_f32_e32 v90, v10
	v_exp_f32_e32 v91, v11
	v_exp_f32_e32 v92, v12
	v_exp_f32_e32 v93, v13
	v_exp_f32_e32 v94, v14
	v_exp_f32_e32 v95, v15
	s_waitcnt vmcnt(3) lgkmcnt(0)
	s_barrier
	v_and_b32_e32 v0, 3, v36
	s_andn2_b64 vcc, exec, s[2:3]
	v_cmp_gt_u32_e64 s[2:3], 32, v247
	v_lshlrev_b32_e32 v240, 4, v246
	v_lshl_add_u32 v252, v248, 2, s27
	v_lshlrev_b32_e32 v212, 4, v0
	s_cbranch_vccnz .LBB0_1032
	s_add_i32 s12, s14, s68
	s_lshl_b32 s12, s12, 19
	s_lshl_b64 s[10:11], s[8:9], 1
	s_and_b32 s12, s12, 0xf00000
	s_add_u32 s10, s12, s10
	v_mov_b32_e32 v213, v221
	s_addc_u32 s11, 0, s11
	v_lshl_add_u64 v[0:1], s[10:11], 0, v[212:213]
	s_lshl_b32 s10, s15, 5
	s_and_b32 s10, s10, 0x1800
	v_lshl_or_b32 v2, v224, 7, s10
	s_add_i32 s10, s69, s14
	s_and_b32 s10, s10, 31
	s_lshl_b32 s12, s10, 19
	s_lshl_b64 s[10:11], s[0:1], 1
	v_mov_b32_e32 v3, v221
	s_add_u32 s10, s10, s12
	v_mov_b32_e32 v32, v221
	v_mov_b32_e32 v33, v221
	v_mov_b32_e32 v46, v221
	v_mov_b32_e32 v47, v221
	v_lshl_add_u64 v[214:215], v[0:1], 0, v[2:3]
	s_addc_u32 s11, s11, 0
	v_mov_b32_e32 v34, v221
	v_mov_b32_e32 v35, v221
	v_mov_b32_e32 v36, v221
	v_mov_b32_e32 v37, v221
	v_mov_b32_e32 v38, v221
	v_mov_b32_e32 v39, v221
	v_mov_b32_e32 v40, v221
	v_mov_b32_e32 v41, v221
	v_mov_b32_e32 v42, v221
	v_mov_b32_e32 v43, v221
	v_mov_b32_e32 v44, v221
	v_mov_b32_e32 v45, v221
	v_mov_b64_e32 v[62:63], v[46:47]
	v_mov_b64_e32 v[16:17], v[32:33]
	v_mov_b64_e32 v[0:1], v[32:33]
	v_lshl_add_u64 v[216:217], s[10:11], 0, v[220:221]
	s_mov_b32 s10, 0
	s_movk_i32 s17, 0x4000
	s_movk_i32 s40, 0x2000
	v_mov_b32_e32 v232, 0
	s_mov_b32 s30, 6
	v_mov_b64_e32 v[60:61], v[44:45]
	v_mov_b64_e32 v[58:59], v[42:43]
	v_mov_b64_e32 v[56:57], v[40:41]
	v_mov_b64_e32 v[54:55], v[38:39]
	v_mov_b64_e32 v[52:53], v[36:37]
	v_mov_b64_e32 v[50:51], v[34:35]
	v_mov_b64_e32 v[48:49], v[32:33]
	v_mov_b64_e32 v[18:19], v[34:35]
	v_mov_b64_e32 v[20:21], v[36:37]
	v_mov_b64_e32 v[22:23], v[38:39]
	v_mov_b64_e32 v[24:25], v[40:41]
	v_mov_b64_e32 v[26:27], v[42:43]
	v_mov_b64_e32 v[28:29], v[44:45]
	v_mov_b64_e32 v[30:31], v[46:47]
	v_mov_b64_e32 v[2:3], v[34:35]
	v_mov_b64_e32 v[4:5], v[36:37]
	v_mov_b64_e32 v[6:7], v[38:39]
	v_mov_b64_e32 v[8:9], v[40:41]
	v_mov_b64_e32 v[10:11], v[42:43]
	v_mov_b64_e32 v[12:13], v[44:45]
	v_mov_b64_e32 v[14:15], v[46:47]
.LBB0_1018:
	v_add_u32_e32 v213, s10, v239
	ds_read_b64_tr_b16 v[208:209], v213 offset:24576
	ds_read_b64_tr_b16 v[210:211], v213 offset:25088
	s_waitcnt lgkmcnt(9)
	v_mfma_f32_32x32x16_bf16 v[128:143], v[204:207], v[172:175], v[64:79]
	v_add_f32_e32 v112, v96, v97
	v_add_f32_e32 v112, v98, v112
	v_add_f32_e32 v112, v99, v112
	v_add_f32_e32 v112, v100, v112
	v_add_f32_e32 v112, v101, v112
	v_cvt_pk_bf16_f32 v164, v96, v97
	v_cvt_pk_bf16_f32 v165, v98, v99
	ds_read_b64_tr_b16 v[204:205], v213 offset:28672
	ds_read_b64_tr_b16 v[206:207], v213 offset:29184
	v_add_f32_e32 v96, v102, v112
	s_waitcnt lgkmcnt(10)
	v_mfma_f32_32x32x16_bf16 v[112:127], v[200:203], v[172:175], v[64:79]
	v_add_f32_e32 v96, v103, v96
	v_add_f32_e32 v96, v104, v96
	v_add_f32_e32 v144, v105, v96
	v_cvt_pk_bf16_f32 v166, v100, v101
	v_cvt_pk_bf16_f32 v167, v102, v103
	ds_read_b64_tr_b16 v[96:97], v213 offset:25600
	ds_read_b64_tr_b16 v[98:99], v213 offset:26112
	s_waitcnt lgkmcnt(11)
	v_mfma_f32_32x32x16_bf16 v[128:143], v[196:199], v[168:171], v[128:143]
	v_add_f32_e32 v100, v106, v144
	v_add_f32_e32 v100, v107, v100
	v_add_f32_e32 v100, v108, v100
	v_add_f32_e32 v144, v109, v100
	v_cvt_pk_bf16_f32 v160, v104, v105
	v_cvt_pk_bf16_f32 v161, v106, v107
	ds_read_b64_tr_b16 v[100:101], v213 offset:29696
	ds_read_b64_tr_b16 v[102:103], v213 offset:30208
	s_waitcnt lgkmcnt(12)
	v_mfma_f32_32x32x16_bf16 v[112:127], v[192:195], v[168:171], v[112:127]
	v_add_f32_e32 v104, v110, v144
	v_add_f32_e32 v104, v111, v104
	v_add_f32_e32 v104, v80, v104
	v_add_f32_e32 v144, v81, v104
	v_cvt_pk_bf16_f32 v162, v108, v109
	v_cvt_pk_bf16_f32 v163, v110, v111
	ds_read_b64_tr_b16 v[104:105], v213 offset:26624
	ds_read_b64_tr_b16 v[106:107], v213 offset:27136
	s_waitcnt lgkmcnt(13)
	v_mfma_f32_32x32x16_bf16 v[128:143], v[188:191], v[156:159], v[128:143]
	v_add_f32_e32 v108, v82, v144
	v_add_f32_e32 v108, v83, v108
	v_add_f32_e32 v108, v84, v108
	v_add_f32_e32 v144, v85, v108
	v_cvt_pk_bf16_f32 v152, v80, v81
	v_cvt_pk_bf16_f32 v153, v82, v83
	ds_read_b64_tr_b16 v[108:109], v213 offset:30720
	ds_read_b64_tr_b16 v[110:111], v213 offset:31232
	s_waitcnt lgkmcnt(14)
	v_mfma_f32_32x32x16_bf16 v[112:127], v[184:187], v[156:159], v[112:127]
	v_add_f32_e32 v80, v86, v144
	v_add_f32_e32 v80, v87, v80
	v_add_f32_e32 v80, v88, v80
	v_add_f32_e32 v80, v89, v80
	v_cvt_pk_bf16_f32 v154, v84, v85
	v_cvt_pk_bf16_f32 v155, v86, v87
	ds_read_b64_tr_b16 v[84:85], v213 offset:27648
	ds_read_b64_tr_b16 v[86:87], v213 offset:28160
	s_waitcnt lgkmcnt(14)
	v_mfma_f32_32x32x16_bf16 v[128:143], v[180:183], v[148:151], v[128:143]
	v_add_f32_e32 v80, v90, v80
	v_add_f32_e32 v80, v91, v80
	v_add_f32_e32 v80, v92, v80
	v_add_f32_e32 v80, v93, v80
	v_cvt_pk_bf16_f32 v144, v88, v89
	v_cvt_pk_bf16_f32 v145, v90, v91
	ds_read_b64_tr_b16 v[88:89], v213 offset:31744
	ds_read_b64_tr_b16 v[90:91], v213 offset:32256
	v_mfma_f32_32x32x16_bf16 v[112:127], v[176:179], v[148:151], v[112:127]
	v_add_f32_e32 v80, v94, v80
	v_add_f32_e32 v80, v95, v80
	v_add_f32_e32 v82, 0, v80
	v_cvt_pk_bf16_f32 v146, v92, v93
	v_cvt_pk_bf16_f32 v147, v94, v95
	v_lshl_add_u64 v[222:223], s[4:5], 0, v[216:217]
	v_lshl_add_u64 v[80:81], v[222:223], 0, s[44:45]
	v_lshl_add_u64 v[218:219], s[4:5], 0, v[214:215]
	s_add_i32 s10, s40, s28
	s_mov_b32 m0, s10
	s_nop 0
	global_load_lds_dwordx4 v[80:81], off
	v_lshl_add_u64 v[80:81], v[218:219], 0, s[46:47]
	s_add_i32 s10, s17, s33
	s_mov_b32 m0, s10
	s_nop 0
	global_load_lds_dwordx4 v[80:81], off
	v_lshl_add_u64 v[80:81], v[218:219], 0, s[48:49]
	s_add_i32 s10, s17, s37
	s_mov_b32 m0, s10
	s_nop 0
	global_load_lds_dwordx4 v[80:81], off
	v_max_f32_e32 v80, v129, v129
	v_max_f32_e32 v81, v128, v128
	v_max_f32_e32 v80, v81, v80
	v_max3_f32 v81, v130, v131, v113
	v_max3_f32 v80, v80, v112, v114
	v_max3_f32 v80, v80, v115, v132
	v_max3_f32 v81, v81, v134, v135
	v_max3_f32 v80, v80, v133, v116
	v_max3_f32 v81, v81, v118, v119
	v_max3_f32 v80, v80, v117, v136
	v_max3_f32 v81, v81, v138, v139
	v_max3_f32 v80, v80, v137, v120
	v_max3_f32 v81, v81, v122, v123
	v_max3_f32 v80, v80, v121, v140
	v_max3_f32 v81, v81, v142, v143
	v_max3_f32 v80, v80, v141, v124
	v_max3_f32 v81, v81, v126, v127
	v_max3_f32 v80, v80, v125, v81
	v_mov_b32_e32 v81, v80
	s_nop 1
	v_permlane32_swap_b32_e32 v80, v81
	v_max_f32_e32 v81, v81, v81
	v_max_f32_e32 v80, v80, v80
	v_max_f32_e32 v80, v80, v81
	v_cmp_lt_f32_e32 vcc, s43, v80
	s_cmp_lg_u64 vcc, 0
	v_add_f32_e32 v225, v232, v82
	s_cselect_b64 s[10:11], -1, 0
	s_cbranch_vccnz .LBB0_1026

.LBB0_1021:
	s_add_i32 s10, s17, 0x2000
	s_cmpk_lg_i32 s17, 0x4000
	s_cselect_b32 s41, s10, 0
	v_add_u32_e32 v226, s40, v239
	ds_read_b64_tr_b16 v[204:205], v226 offset:24576
	ds_read_b64_tr_b16 v[206:207], v226 offset:25088
	v_mfma_f32_32x32x16_bf16 v[96:111], v[80:83], v[172:175], v[64:79]
	v_add_f32_e32 v84, v128, v129
	v_add_f32_e32 v84, v130, v84
	v_add_f32_e32 v84, v131, v84
	v_add_f32_e32 v84, v132, v84
	v_add_f32_e32 v84, v133, v84
	v_cvt_pk_bf16_f32 v164, v128, v129
	v_cvt_pk_bf16_f32 v165, v130, v131
	ds_read_b64_tr_b16 v[208:209], v226 offset:28672
	ds_read_b64_tr_b16 v[210:211], v226 offset:29184
	v_add_f32_e32 v80, v134, v84
	v_add_f32_e32 v80, v135, v80
	v_add_f32_e32 v80, v136, v80
	v_add_f32_e32 v144, v137, v80
	v_mfma_f32_32x32x16_bf16 v[80:95], v[196:199], v[172:175], v[64:79]
	v_cvt_pk_bf16_f32 v166, v132, v133
	v_cvt_pk_bf16_f32 v167, v134, v135
	ds_read_b64_tr_b16 v[128:129], v226 offset:25600
	ds_read_b64_tr_b16 v[130:131], v226 offset:26112
	v_mfma_f32_32x32x16_bf16 v[96:111], v[200:203], v[168:171], v[96:111]
	v_add_f32_e32 v132, v138, v144
	v_add_f32_e32 v132, v139, v132
	v_add_f32_e32 v132, v140, v132
	v_add_f32_e32 v144, v141, v132
	v_cvt_pk_bf16_f32 v160, v136, v137
	v_cvt_pk_bf16_f32 v161, v138, v139
	ds_read_b64_tr_b16 v[132:133], v226 offset:29696
	ds_read_b64_tr_b16 v[134:135], v226 offset:30208
	v_mfma_f32_32x32x16_bf16 v[80:95], v[192:195], v[168:171], v[80:95]
	v_add_f32_e32 v136, v142, v144
	v_add_f32_e32 v136, v143, v136
	v_add_f32_e32 v136, v112, v136
	v_add_f32_e32 v144, v113, v136
	v_cvt_pk_bf16_f32 v162, v140, v141
	v_cvt_pk_bf16_f32 v163, v142, v143
	ds_read_b64_tr_b16 v[136:137], v226 offset:26624
	ds_read_b64_tr_b16 v[138:139], v226 offset:27136
	v_mfma_f32_32x32x16_bf16 v[96:111], v[188:191], v[156:159], v[96:111]
	v_add_f32_e32 v140, v114, v144
	v_add_f32_e32 v140, v115, v140
	v_add_f32_e32 v140, v116, v140
	v_add_f32_e32 v140, v117, v140
	v_cvt_pk_bf16_f32 v152, v112, v113
	v_cvt_pk_bf16_f32 v153, v114, v115
	ds_read_b64_tr_b16 v[112:113], v226 offset:30720
	ds_read_b64_tr_b16 v[114:115], v226 offset:31232
	v_mfma_f32_32x32x16_bf16 v[80:95], v[184:187], v[156:159], v[80:95]
	v_add_f32_e32 v140, v118, v140
	v_add_f32_e32 v140, v119, v140
	v_add_f32_e32 v140, v120, v140
	v_add_f32_e32 v140, v121, v140
	v_cvt_pk_bf16_f32 v154, v116, v117
	v_cvt_pk_bf16_f32 v155, v118, v119
	ds_read_b64_tr_b16 v[116:117], v226 offset:27648
	ds_read_b64_tr_b16 v[118:119], v226 offset:28160
	v_mfma_f32_32x32x16_bf16 v[96:111], v[180:183], v[148:151], v[96:111]
	v_add_f32_e32 v140, v122, v140
	v_add_f32_e32 v140, v123, v140
	v_add_f32_e32 v140, v124, v140
	v_add_f32_e32 v140, v125, v140
	v_cvt_pk_bf16_f32 v144, v120, v121
	v_cvt_pk_bf16_f32 v145, v122, v123
	ds_read_b64_tr_b16 v[120:121], v226 offset:31744
	ds_read_b64_tr_b16 v[122:123], v226 offset:32256
	v_mfma_f32_32x32x16_bf16 v[80:95], v[176:179], v[148:151], v[80:95]
	v_add_f32_e32 v140, v126, v140
	v_add_f32_e32 v140, v127, v140
	v_add_f32_e32 v140, 0, v140
	v_cvt_pk_bf16_f32 v146, v124, v125
	v_cvt_pk_bf16_f32 v147, v126, v127
	s_mov_b64 s[10:11], 0x1840a000
	v_lshl_add_u64 v[124:125], v[222:223], 0, s[10:11]
	s_add_i32 s10, s17, s28
	s_mov_b32 m0, s10
	s_nop 0
	global_load_lds_dwordx4 v[124:125], off
	s_mov_b64 s[10:11], 0x19406000
	v_lshl_add_u64 v[124:125], v[218:219], 0, s[10:11]
	s_add_i32 s10, s41, s33
	s_mov_b32 m0, s10
	s_nop 0
	global_load_lds_dwordx4 v[124:125], off
	s_mov_b64 s[10:11], 0x19486000
	v_lshl_add_u64 v[124:125], v[218:219], 0, s[10:11]
	s_add_i32 s10, s41, s37
	s_mov_b32 m0, s10
	s_nop 0
	global_load_lds_dwordx4 v[124:125], off
	v_max_f32_e32 v124, v97, v97
	v_max_f32_e32 v125, v96, v96
	v_max_f32_e32 v124, v125, v124
	v_max3_f32 v125, v98, v99, v81
	v_max3_f32 v124, v124, v80, v82
	v_max3_f32 v124, v124, v83, v100
	v_max3_f32 v125, v125, v102, v103
	v_max3_f32 v124, v124, v101, v84
	v_max3_f32 v125, v125, v86, v87
	v_max3_f32 v124, v124, v85, v104
	v_max3_f32 v125, v125, v106, v107
	v_max3_f32 v124, v124, v105, v88
	v_max3_f32 v125, v125, v90, v91
	v_max3_f32 v124, v124, v89, v108
	v_max3_f32 v125, v125, v110, v111
	v_max3_f32 v124, v124, v109, v92
	v_max3_f32 v125, v125, v94, v95
	v_max3_f32 v124, v124, v93, v125
	v_mov_b32_e32 v125, v124
	s_nop 1
	v_permlane32_swap_b32_e32 v124, v125
	v_max_f32_e32 v125, v125, v125
	v_max_f32_e32 v124, v124, v124
	v_max_f32_e32 v124, v124, v125
	v_cmp_lt_f32_e32 vcc, s43, v124
	s_cmp_lg_u64 vcc, 0
	v_add_f32_e32 v232, v225, v140
	s_cselect_b64 s[10:11], -1, 0
	s_cbranch_vccnz .LBB0_1029

;   #define RESC() do{ if(resc){ asm volatile("s_waitcnt lgkmcnt(0)":::"memory"); \
;       _Pragma("unroll") for(int d_=0;d_<4;++d_) _Pragma("unroll") for(int r=0;r<16;++r)o[d_][r]*=wsf[crow(r,hi)]; } }while(0)
;   #define ROT() do{sl_prev=sl_cur;sl_cur=sl_next;sl_next=(sl_next==(NSLOT-1)*SLOTB)?0:sl_next+SLOTB;}while(0)
;   #define ENDW(tt) do{ if((tt)+3<NT){WAIT_BAR(3);} else if((tt)+2<NT){WAIT_BAR(2);} else {WAIT_BAR(0);} }while(0)
; template<int THRL> __device__ __forceinline__ void attn_unit(int qb,const bf16*Q,const bf16*__restrict__ K,const bf16*__restrict__ V,bf16*O,char*shm){
;     ...
;   for(;t+1<NT;t+=2){
;     STEP(pB0,pB1,pA0,pA1,t,(t+3<NT),(t+1<NT),(t+1<NT));       ENDW(t);   RESC(); ROT();
;     STEP(pA0,pA1,pB0,pB1,t+1,(t+4<NT),(t+2<NT),(t+2<NT));     ENDW(t+1); RESC(); ROT();
.LBB0_1041:
	v_add_u32_e32 v212, s17, v239
	ds_read_b64_tr_b16 v[208:209], v212 offset:24576
	ds_read_b64_tr_b16 v[210:211], v212 offset:25088
	s_waitcnt lgkmcnt(9)
	v_mfma_f32_32x32x16_bf16 v[128:143], v[204:207], v[172:175], v[64:79]
	v_add_f32_e32 v112, v96, v97
	v_add_f32_e32 v112, v98, v112
	v_add_f32_e32 v112, v99, v112
	v_add_f32_e32 v112, v100, v112
	v_add_f32_e32 v112, v101, v112
	v_cvt_pk_bf16_f32 v164, v96, v97
	v_cvt_pk_bf16_f32 v165, v98, v99
	ds_read_b64_tr_b16 v[204:205], v212 offset:28672
	ds_read_b64_tr_b16 v[206:207], v212 offset:29184
	v_add_f32_e32 v96, v102, v112
	s_waitcnt lgkmcnt(10)
	v_mfma_f32_32x32x16_bf16 v[112:127], v[200:203], v[172:175], v[64:79]
	v_add_f32_e32 v96, v103, v96
	v_add_f32_e32 v96, v104, v96
	v_add_f32_e32 v144, v105, v96
	v_cvt_pk_bf16_f32 v166, v100, v101
	v_cvt_pk_bf16_f32 v167, v102, v103
	ds_read_b64_tr_b16 v[96:97], v212 offset:25600
	ds_read_b64_tr_b16 v[98:99], v212 offset:26112
	s_waitcnt lgkmcnt(11)
	v_mfma_f32_32x32x16_bf16 v[128:143], v[196:199], v[168:171], v[128:143]
	v_add_f32_e32 v100, v106, v144
	v_add_f32_e32 v100, v107, v100
	v_add_f32_e32 v100, v108, v100
	v_add_f32_e32 v144, v109, v100
	v_cvt_pk_bf16_f32 v160, v104, v105
	v_cvt_pk_bf16_f32 v161, v106, v107
	ds_read_b64_tr_b16 v[100:101], v212 offset:29696
	ds_read_b64_tr_b16 v[102:103], v212 offset:30208
	s_waitcnt lgkmcnt(12)
	v_mfma_f32_32x32x16_bf16 v[112:127], v[192:195], v[168:171], v[112:127]
	v_add_f32_e32 v104, v110, v144
	v_add_f32_e32 v104, v111, v104
	v_add_f32_e32 v104, v80, v104
	v_add_f32_e32 v144, v81, v104
	v_cvt_pk_bf16_f32 v162, v108, v109
	v_cvt_pk_bf16_f32 v163, v110, v111
	ds_read_b64_tr_b16 v[104:105], v212 offset:26624
	ds_read_b64_tr_b16 v[106:107], v212 offset:27136
	s_waitcnt lgkmcnt(13)
	v_mfma_f32_32x32x16_bf16 v[128:143], v[188:191], v[156:159], v[128:143]
	v_add_f32_e32 v108, v82, v144
	v_add_f32_e32 v108, v83, v108
	v_add_f32_e32 v108, v84, v108
	v_add_f32_e32 v108, v85, v108
	v_cvt_pk_bf16_f32 v152, v80, v81
	v_cvt_pk_bf16_f32 v153, v82, v83
	ds_read_b64_tr_b16 v[80:81], v212 offset:30720
	ds_read_b64_tr_b16 v[82:83], v212 offset:31232
	s_waitcnt lgkmcnt(14)
	v_mfma_f32_32x32x16_bf16 v[112:127], v[184:187], v[156:159], v[112:127]
	v_add_f32_e32 v108, v86, v108
	v_add_f32_e32 v108, v87, v108
	v_add_f32_e32 v108, v88, v108
	v_add_f32_e32 v108, v89, v108
	v_cvt_pk_bf16_f32 v154, v84, v85
	v_cvt_pk_bf16_f32 v155, v86, v87
	ds_read_b64_tr_b16 v[84:85], v212 offset:27648
	ds_read_b64_tr_b16 v[86:87], v212 offset:28160
	s_waitcnt lgkmcnt(14)
	v_mfma_f32_32x32x16_bf16 v[128:143], v[180:183], v[148:151], v[128:143]
	v_add_f32_e32 v108, v90, v108
	v_add_f32_e32 v108, v91, v108
	v_add_f32_e32 v108, v92, v108
	v_add_f32_e32 v108, v93, v108
	v_cvt_pk_bf16_f32 v144, v88, v89
	v_cvt_pk_bf16_f32 v145, v90, v91
	ds_read_b64_tr_b16 v[88:89], v212 offset:31744
	ds_read_b64_tr_b16 v[90:91], v212 offset:32256
	v_mfma_f32_32x32x16_bf16 v[112:127], v[176:179], v[148:151], v[112:127]
	v_add_f32_e32 v108, v94, v108
	v_add_f32_e32 v108, v95, v108
	v_add_f32_e32 v108, 0, v108
	v_cvt_pk_bf16_f32 v146, v92, v93
	v_cvt_pk_bf16_f32 v147, v94, v95
	s_add_i32 s0, s40, 1
	s_cmp_ge_u32 s0, s39
	s_cselect_b64 s[8:9], -1, 0
	s_and_b64 vcc, exec, s[8:9]
	v_lshl_add_u64 v[228:229], v[224:225], 0, s[10:11]
	s_cbranch_vccnz .LBB0_1043
	s_mov_b64 s[0:1], 0x18406000
	v_lshl_add_u64 v[92:93], v[228:229], 0, s[0:1]
	s_add_i32 s0, s41, s28
	s_mov_b32 m0, s0
	s_nop 0
	global_load_lds_dwordx4 v[92:93], off
; __device__ __forceinline__ void cmask(f32x16&p0,f32x16&p1,int jb,int qrel,int hi){
;   const float NEG=-INFINITY; int kb=64*jb+4*hi;
;   #pragma unroll
;   for(int r=0;r<16;++r){int kv=kb+(r&3)+8*(r>>2); if(kv>qrel)p0[r]=NEG; if(kv+32>qrel)p1[r]=NEG;}
; }
; __device__ __forceinline__ void glds16(const void*gsrc,unsigned lds_dst){unsigned keep;
;   asm volatile("s_mov_b32 %0, m0\n\ts_mov_b32 m0, %2\n\ts_nop 0\n\tglobal_load_lds_dwordx4 %1, off\n\ts_mov_b32 m0, %0":"=&s"(keep):"v"(gsrc),"s"(lds_dst):"memory");}
.LBB0_1043:
	v_lshl_add_u64 v[226:227], v[222:223], 0, s[10:11]
	s_mov_b64 s[0:1], 0x19402000
	v_lshl_add_u64 v[92:93], v[226:227], 0, s[0:1]
	s_add_i32 s0, s42, s33
	s_mov_b32 m0, s0
	s_nop 0
	global_load_lds_dwordx4 v[92:93], off
	s_mov_b64 s[0:1], 0x19482000
	v_lshl_add_u64 v[92:93], v[226:227], 0, s[0:1]
	s_add_i32 s0, s42, s37
	s_mov_b32 m0, s0
	s_nop 0
	global_load_lds_dwordx4 v[92:93], off
	s_add_i32 s14, s50, s40
	s_add_i32 s0, s14, 2
	s_cmp_lt_i32 s0, 0
	s_cbranch_scc1 .LBB0_1045
	v_add_u32_e32 v92, 32, v233
	v_cmp_le_i32_e32 vcc, v92, v241
	v_add_u32_e32 v92, 33, v233
	s_nop 0
	v_cndmask_b32_e32 v112, v234, v112, vcc
	v_cmp_lt_i32_e32 vcc, v233, v241
	s_nop 1
	v_cndmask_b32_e32 v129, v234, v129, vcc
	v_cmp_le_i32_e32 vcc, v233, v241
	s_nop 1
	v_cndmask_b32_e32 v128, v234, v128, vcc
	v_cmp_le_i32_e32 vcc, v92, v241
	v_add_u32_e32 v92, 2, v233
	s_nop 0
	v_cndmask_b32_e32 v113, v234, v113, vcc
	v_cmp_le_i32_e32 vcc, v92, v241
	v_add_u32_e32 v92, 34, v233
	s_nop 0
	v_cndmask_b32_e32 v130, v234, v130, vcc
	v_cmp_le_i32_e32 vcc, v92, v241
	v_add_u32_e32 v92, 3, v233
	s_nop 0
	v_cndmask_b32_e32 v114, v234, v114, vcc
	v_cmp_le_i32_e32 vcc, v92, v241
	v_add_u32_e32 v92, 35, v233
	s_nop 0
	v_cndmask_b32_e32 v131, v234, v131, vcc
	v_cmp_le_i32_e32 vcc, v92, v241
	v_add_u32_e32 v92, 8, v233
	s_nop 0
	v_cndmask_b32_e32 v115, v234, v115, vcc
	v_cmp_le_i32_e32 vcc, v92, v241
	v_add_u32_e32 v92, 40, v233
	s_nop 0
	v_cndmask_b32_e32 v132, v234, v132, vcc
	v_cmp_le_i32_e32 vcc, v92, v241
	v_add_u32_e32 v92, 9, v233
	s_nop 0
	v_cndmask_b32_e32 v116, v234, v116, vcc
	v_cmp_le_i32_e32 vcc, v92, v241
	v_add_u32_e32 v92, 41, v233
	s_nop 0
	v_cndmask_b32_e32 v133, v234, v133, vcc
	v_cmp_le_i32_e32 vcc, v92, v241
	v_add_u32_e32 v92, 10, v233
	s_nop 0
	v_cndmask_b32_e32 v117, v234, v117, vcc
	v_cmp_le_i32_e32 vcc, v92, v241
	v_add_u32_e32 v92, 42, v233
	s_nop 0
	v_cndmask_b32_e32 v134, v234, v134, vcc
	v_cmp_le_i32_e32 vcc, v92, v241
	v_add_u32_e32 v92, 11, v233
	s_nop 0
	v_cndmask_b32_e32 v118, v234, v118, vcc
	v_cmp_le_i32_e32 vcc, v92, v241
	v_add_u32_e32 v92, 43, v233
	s_nop 0
	v_cndmask_b32_e32 v135, v234, v135, vcc
	v_cmp_le_i32_e32 vcc, v92, v241
	v_add_u32_e32 v92, 16, v233
	s_nop 0
	v_cndmask_b32_e32 v119, v234, v119, vcc
	v_cmp_le_i32_e32 vcc, v92, v241
	v_add_u32_e32 v92, 48, v233
	s_nop 0
	v_cndmask_b32_e32 v136, v234, v136, vcc
	v_cmp_le_i32_e32 vcc, v92, v241
	v_add_u32_e32 v92, 17, v233
	s_nop 0
	v_cndmask_b32_e32 v120, v234, v120, vcc
	v_cmp_le_i32_e32 vcc, v92, v241
	v_add_u32_e32 v92, 49, v233
	s_nop 0
	v_cndmask_b32_e32 v137, v234, v137, vcc
	v_cmp_le_i32_e32 vcc, v92, v241
	v_add_u32_e32 v92, 18, v233
	s_nop 0
	v_cndmask_b32_e32 v121, v234, v121, vcc
	v_cmp_le_i32_e32 vcc, v92, v241
	v_add_u32_e32 v92, 50, v233
	s_nop 0
	v_cndmask_b32_e32 v138, v234, v138, vcc
	v_cmp_le_i32_e32 vcc, v92, v241
	v_add_u32_e32 v92, 19, v233
	s_nop 0
	v_cndmask_b32_e32 v122, v234, v122, vcc
	v_cmp_le_i32_e32 vcc, v92, v241
	v_add_u32_e32 v92, 51, v233
	s_nop 0
	v_cndmask_b32_e32 v139, v234, v139, vcc
	v_cmp_le_i32_e32 vcc, v92, v241
	v_add_u32_e32 v92, 24, v233
	s_nop 0
	v_cndmask_b32_e32 v123, v234, v123, vcc
	v_cmp_le_i32_e32 vcc, v92, v241
	v_add_u32_e32 v92, 56, v233
	s_nop 0
	v_cndmask_b32_e32 v140, v234, v140, vcc
	v_cmp_le_i32_e32 vcc, v92, v241
	v_add_u32_e32 v92, 25, v233
	s_nop 0
	v_cndmask_b32_e32 v124, v234, v124, vcc
	v_cmp_le_i32_e32 vcc, v92, v241
	v_add_u32_e32 v92, 57, v233
	s_nop 0
	v_cndmask_b32_e32 v141, v234, v141, vcc
	v_cmp_le_i32_e32 vcc, v92, v241
	v_add_u32_e32 v92, 26, v233
	s_nop 0
	v_cndmask_b32_e32 v125, v234, v125, vcc
	v_cmp_le_i32_e32 vcc, v92, v241
	v_add_u32_e32 v92, 58, v233
	s_nop 0
	v_cndmask_b32_e32 v142, v234, v142, vcc
	v_cmp_le_i32_e32 vcc, v92, v241
	v_add_u32_e32 v92, 27, v233
	s_nop 0
	v_cndmask_b32_e32 v126, v234, v126, vcc
	v_cmp_le_i32_e32 vcc, v92, v241
	v_add_u32_e32 v92, 59, v233
	s_nop 0
	v_cndmask_b32_e32 v143, v234, v143, vcc
	v_cmp_le_i32_e32 vcc, v92, v241
	s_nop 1
	v_cndmask_b32_e32 v127, v234, v127, vcc

.LBB0_1050:
	v_add_u32_e32 v236, s41, v239
	ds_read_b64_tr_b16 v[212:213], v236 offset:24576
	ds_read_b64_tr_b16 v[214:215], v236 offset:25088
	v_mfma_f32_32x32x16_bf16 v[96:111], v[204:207], v[172:175], v[64:79]
	v_add_f32_e32 v80, v128, v129
	v_add_f32_e32 v80, v130, v80
	v_add_f32_e32 v80, v131, v80
	v_add_f32_e32 v80, v132, v80
	v_add_f32_e32 v80, v133, v80
	v_cvt_pk_bf16_f32 v164, v128, v129
	v_cvt_pk_bf16_f32 v165, v130, v131
	ds_read_b64_tr_b16 v[216:217], v236 offset:28672
	ds_read_b64_tr_b16 v[218:219], v236 offset:29184
	v_add_f32_e32 v80, v134, v80
	v_add_f32_e32 v80, v135, v80
	v_add_f32_e32 v80, v136, v80
	v_add_f32_e32 v128, v137, v80
	v_mfma_f32_32x32x16_bf16 v[80:95], v[200:203], v[172:175], v[64:79]
	v_cvt_pk_bf16_f32 v166, v132, v133
	v_cvt_pk_bf16_f32 v167, v134, v135
	ds_read_b64_tr_b16 v[208:209], v236 offset:25600
	ds_read_b64_tr_b16 v[210:211], v236 offset:26112
	v_mfma_f32_32x32x16_bf16 v[96:111], v[196:199], v[168:171], v[96:111]
	v_add_f32_e32 v128, v138, v128
	v_add_f32_e32 v128, v139, v128
	v_add_f32_e32 v128, v140, v128
	v_add_f32_e32 v128, v141, v128
	v_cvt_pk_bf16_f32 v160, v136, v137
	v_cvt_pk_bf16_f32 v161, v138, v139
	ds_read_b64_tr_b16 v[132:133], v236 offset:29696
	ds_read_b64_tr_b16 v[134:135], v236 offset:30208
	v_mfma_f32_32x32x16_bf16 v[80:95], v[192:195], v[168:171], v[80:95]
	v_add_f32_e32 v128, v142, v128
	v_add_f32_e32 v128, v143, v128
	v_add_f32_e32 v128, v112, v128
	v_add_f32_e32 v136, v113, v128
	v_cvt_pk_bf16_f32 v162, v140, v141
	v_cvt_pk_bf16_f32 v163, v142, v143
	ds_read_b64_tr_b16 v[128:129], v236 offset:26624
	ds_read_b64_tr_b16 v[130:131], v236 offset:27136
	v_mfma_f32_32x32x16_bf16 v[96:111], v[188:191], v[156:159], v[96:111]
	v_add_f32_e32 v136, v114, v136
	v_add_f32_e32 v136, v115, v136
	v_add_f32_e32 v136, v116, v136
	v_add_f32_e32 v136, v117, v136
	v_cvt_pk_bf16_f32 v152, v112, v113
	v_cvt_pk_bf16_f32 v153, v114, v115
	ds_read_b64_tr_b16 v[112:113], v236 offset:30720
	ds_read_b64_tr_b16 v[114:115], v236 offset:31232
	v_mfma_f32_32x32x16_bf16 v[80:95], v[184:187], v[156:159], v[80:95]
	v_add_f32_e32 v136, v118, v136
	v_add_f32_e32 v136, v119, v136
	v_add_f32_e32 v136, v120, v136
	v_add_f32_e32 v136, v121, v136
	v_cvt_pk_bf16_f32 v154, v116, v117
	v_cvt_pk_bf16_f32 v155, v118, v119
	ds_read_b64_tr_b16 v[116:117], v236 offset:27648
	ds_read_b64_tr_b16 v[118:119], v236 offset:28160
	v_mfma_f32_32x32x16_bf16 v[96:111], v[180:183], v[148:151], v[96:111]
	v_add_f32_e32 v136, v122, v136
	v_add_f32_e32 v136, v123, v136
	v_add_f32_e32 v136, v124, v136
	v_add_f32_e32 v136, v125, v136
	v_cvt_pk_bf16_f32 v144, v120, v121
	v_cvt_pk_bf16_f32 v145, v122, v123
	ds_read_b64_tr_b16 v[120:121], v236 offset:31744
	ds_read_b64_tr_b16 v[122:123], v236 offset:32256
	v_mfma_f32_32x32x16_bf16 v[80:95], v[176:179], v[148:151], v[80:95]
	v_add_f32_e32 v136, v126, v136
	v_add_f32_e32 v136, v127, v136
	v_add_f32_e32 v136, 0, v136
	v_cvt_pk_bf16_f32 v146, v124, v125
	v_cvt_pk_bf16_f32 v147, v126, v127
	s_add_i32 s30, s40, 2
	s_cmp_ge_u32 s30, s39
	s_cselect_b64 s[12:13], -1, 0
	s_and_b64 vcc, exec, s[12:13]
	s_cbranch_vccnz .LBB0_1052
	v_lshl_add_u64 v[124:125], v[228:229], 0, s[44:45]
	s_add_i32 s0, s42, s28
	s_mov_b32 m0, s0
	s_nop 0
	global_load_lds_dwordx4 v[124:125], off
.LBB0_1052:
	s_add_i32 s0, s42, 0x2000
	s_cmpk_lg_i32 s42, 0x4000
	s_cselect_b32 s41, s0, 0
	s_cmp_lt_u32 s40, s39
	s_cselect_b64 s[16:17], -1, 0
	s_cmp_ge_u32 s40, s39
	s_cbranch_scc1 .LBB0_1054
	v_lshl_add_u64 v[124:125], v[226:227], 0, s[46:47]
	s_add_i32 s0, s41, s33
	s_mov_b32 m0, s0
	s_nop 0
	global_load_lds_dwordx4 v[124:125], off
	v_lshl_add_u64 v[126:127], v[226:227], 0, s[48:49]
	s_add_i32 s1, s41, s37
	s_mov_b32 m0, s1
	s_nop 0
	global_load_lds_dwordx4 v[126:127], off
